# row-epilogue (in-proj/kv-up/q-up/b-gate GEMMs): the eight per-row partial-sum records are loaded with a single wait instead of a load-wait per row
# baseline (speedup 1.0000x reference)
.LBB0_419:
	v_lshl_add_u32 v178, s36, 8, v194
	v_ashrrev_i32_e32 v179, 31, v178
	v_or_b32_e32 v176, 16, v178
	v_ashrrev_i32_e32 v177, 31, v176
	v_or_b32_e32 v174, 32, v178
	v_ashrrev_i32_e32 v175, 31, v174
	v_or_b32_e32 v172, 48, v178
	v_ashrrev_i32_e32 v173, 31, v172
	v_add_u32_e32 v130, 0x80, v178
	v_ashrrev_i32_e32 v131, 31, v130
	v_mov_b32_e32 v132, 0
	v_mov_b32_e32 v180, 0
	v_mov_b32_e32 v181, 0
	v_mov_b32_e32 v133, 0
	v_mov_b32_e32 v128, 0
	v_mov_b32_e32 v184, 0
	v_mov_b32_e32 v185, 0
	v_mov_b32_e32 v129, 0
	v_mov_b32_e32 v138, 0
	v_mov_b32_e32 v182, 0
	v_mov_b32_e32 v183, 0
	v_mov_b32_e32 v139, 0
	v_mov_b32_e32 v134, 0
	v_mov_b32_e32 v186, 0
	v_mov_b32_e32 v187, 0
	v_mov_b32_e32 v135, 0
	v_mov_b32_e32 v144, 0
	v_mov_b32_e32 v136, 0
	v_mov_b32_e32 v137, 0
	v_mov_b32_e32 v145, 0
	v_mov_b32_e32 v140, 0
	v_mov_b32_e32 v188, 0
	v_mov_b32_e32 v189, 0
	v_mov_b32_e32 v141, 0
	v_mov_b32_e32 v150, 0
	v_mov_b32_e32 v190, 0
	v_mov_b32_e32 v191, 0
	v_mov_b32_e32 v151, 0
	v_mov_b32_e32 v146, 0
	v_mov_b32_e32 v192, 0
	v_mov_b32_e32 v193, 0
	v_mov_b32_e32 v147, 0
	s_and_saveexec_b64 s[50:51], s[46:47]
	s_cbranch_execz .LBB0_435
	v_lshlrev_b64 v[142:143], 6, v[178:179]
	v_lshl_add_u64 v[142:143], v[166:167], 0, v[142:143]
	v_add_co_u32_e32 v148, vcc, 0x2000, v142
	s_nop 1
	v_addc_co_u32_e32 v149, vcc, 0, v143, vcc
	global_load_dwordx4 v[132:135], v[142:143], off
	global_load_dwordx4 v[228:231], v[142:143], off offset:1024
	global_load_dwordx4 v[138:141], v[142:143], off offset:2048
	global_load_dwordx4 v[208:211], v[142:143], off offset:3072
	global_load_dwordx4 v[144:147], v[148:149], off
	global_load_dwordx4 v[212:215], v[148:149], off offset:1024
	global_load_dwordx4 v[150:153], v[148:149], off offset:2048
	global_load_dwordx4 v[216:219], v[148:149], off offset:3072
	s_waitcnt vmcnt(0)
	v_mov_b32_e32 v180, v133
	v_mov_b32_e32 v181, v134
	v_mov_b32_e32 v133, v135
	v_mov_b32_e32 v182, v139
	v_mov_b32_e32 v183, v140
	v_mov_b32_e32 v139, v141
	v_mov_b32_e32 v136, v145
	v_mov_b32_e32 v137, v146
	v_mov_b32_e32 v145, v147
	v_mov_b32_e32 v190, v151
	v_mov_b32_e32 v191, v152
	v_mov_b32_e32 v151, v153
	v_mov_b32_e32 v128, v228
	v_mov_b32_e32 v184, v229
	v_mov_b32_e32 v185, v230
	v_mov_b32_e32 v129, v231
	v_mov_b32_e32 v134, v208
	v_mov_b32_e32 v186, v209
	v_mov_b32_e32 v187, v210
	v_mov_b32_e32 v135, v211
	v_mov_b32_e32 v140, v212
	v_mov_b32_e32 v188, v213
	v_mov_b32_e32 v189, v214
	v_mov_b32_e32 v141, v215
	v_mov_b32_e32 v146, v216
	v_mov_b32_e32 v192, v217
	v_mov_b32_e32 v193, v218
	v_mov_b32_e32 v147, v219
